# gMLP group loop: u loads issued at the top of the group (before LDS staging)
# baseline (speedup 1.0000x reference)
; #define LAS __attribute__((address_space(3)))
; DI unsigned cvtpk(float lo, float hi) { f32x2_t v = {lo, hi}; bf16x2_t b = __builtin_convertvector(v, bf16x2_t); return __builtin_bit_cast(unsigned, b); }
; DI float bflo(unsigned w) { return __uint_as_float(w << 16); }
; DI float bfhi(unsigned w) { return __uint_as_float(w & 0xffff0000u); }
; DI void gmlp_unit(LAS char* lds, bf16_t* zU, const bf16_t* zV, const float* g_ln, const float* b_ln, const bf16_t* Wb, const float* b_sp, int R0, bool dummy = false) {
;     ...
;     for (int g = 0; g < 4; ++g) {
;         __syncthreads();
; #pragma unroll
;         for (int i = 0; i < 4; ++i) { const int s = lt + 32 * i;
;             *(LAS u32x4*)(Wl + s * WP + lc8 * 2) = pw[i];
;             const u32x4 w = pv[i]; float v[8] = {bflo(w.x), bfhi(w.x), bflo(w.y), bfhi(w.y), bflo(w.z), bfhi(w.z), bflo(w.w), bfhi(w.w)};
;             const float mu = St[2 * s], rsd = St[2 * s + 1];
; #pragma unroll
;             for (int e = 0; e < 8; ++e) v[e] = (v[e] - mu) * rsd * pg[e >> 2][e & 3] + pb[e >> 2][e & 3];
;             u32x4 o; o.x = cvtpk(v[0], v[1]); o.y = cvtpk(v[2], v[3]); o.z = cvtpk(v[4], v[5]); o.w = cvtpk(v[6], v[7]); *(LAS u32x4*)(Vn + s * VP + lc8 * 2) = o; }
;         __syncthreads();
;         if (g + 1 < 4) GM_FETCH(g + 1);
;         u32x2 uw[2][4]; float bs[2];
; #pragma unroll
;         for (int tb = 0; tb < 2; ++tb) { const int t = 32 * (2 * tp + tb) + r; bs[tb] = b_sp[g * 128 + t]; const bf16_t* up = zU + (size_t)(R0 + t) * 512 + g * 128 + 32 * cb + 4 * h;
; #pragma unroll
;             for (int k = 0; k < 4; ++k) uw[tb][k] = *(const u32x2*)(up + 8 * k); }
.LBB0_530:
	v_lshl_add_u64 v[218:219], s[86:87], 0, v[192:193]
	v_lshl_add_u64 v[2:3], v[184:185], 0, s[54:55]
	global_load_dwordx2 v[228:229], v[218:219], off offset:-32
	global_load_dwordx2 v[226:227], v[218:219], off offset:-16
	global_load_dwordx2 v[224:225], v[218:219], off
	global_load_dwordx2 v[222:223], v[218:219], off offset:16
	global_load_dword v220, v[2:3], off offset:-128
	global_load_dword v208, v[2:3], off
	v_lshl_add_u64 v[206:207], s[86:87], 0, v[196:197]
	global_load_dwordx2 v[216:217], v[206:207], off offset:-32
	global_load_dwordx2 v[214:215], v[206:207], off offset:-16
	global_load_dwordx2 v[212:213], v[206:207], off
	global_load_dwordx2 v[210:211], v[206:207], off offset:16
	s_add_i32 s6, 0, 0x12800
	s_waitcnt lgkmcnt(0)
	s_barrier
	ds_write_b128 v239, v[34:37]
	v_add_u32_e32 v1, s6, v234
	ds_read_b64 v[2:3], v1
	v_lshlrev_b32_e32 v4, 16, v38
	v_and_b32_e32 v5, 0xffff0000, v38
	v_lshlrev_b32_e32 v6, 16, v39
	v_and_b32_e32 v7, 0xffff0000, v39
	v_lshlrev_b32_e32 v8, 16, v40
	v_and_b32_e32 v9, 0xffff0000, v40
	v_lshlrev_b32_e32 v10, 16, v41
	v_and_b32_e32 v11, 0xffff0000, v41
	s_waitcnt lgkmcnt(0)
	v_pk_add_f32 v[4:5], v[4:5], v[2:3] op_sel_hi:[1,0] neg_lo:[0,1] neg_hi:[0,1]
	v_pk_add_f32 v[6:7], v[6:7], v[2:3] op_sel_hi:[1,0] neg_lo:[0,1] neg_hi:[0,1]
	v_pk_add_f32 v[8:9], v[8:9], v[2:3] op_sel_hi:[1,0] neg_lo:[0,1] neg_hi:[0,1]
	v_pk_add_f32 v[10:11], v[10:11], v[2:3] op_sel_hi:[1,0] neg_lo:[0,1] neg_hi:[0,1]
	v_pk_mul_f32 v[4:5], v[2:3], v[4:5] op_sel:[1,0]
	v_pk_mul_f32 v[6:7], v[2:3], v[6:7] op_sel:[1,0]
	v_pk_mul_f32 v[8:9], v[2:3], v[8:9] op_sel:[1,0]
	v_pk_mul_f32 v[2:3], v[2:3], v[10:11] op_sel:[1,0]
	v_pk_fma_f32 v[4:5], v[70:71], v[4:5], v[78:79]
	v_pk_fma_f32 v[6:7], v[72:73], v[6:7], v[80:81]
	v_pk_fma_f32 v[8:9], v[66:67], v[8:9], v[74:75]
	v_pk_fma_f32 v[10:11], v[68:69], v[2:3], v[76:77]
	v_cvt_pk_bf16_f32 v2, v4, v5
	v_cvt_pk_bf16_f32 v3, v6, v7
	v_cvt_pk_bf16_f32 v4, v8, v9
	v_cvt_pk_bf16_f32 v5, v10, v11
	v_add_u32_e32 v1, v230, v235
	ds_write_b128 v1, v[2:5] offset:34816
	ds_write_b128 v239, v[42:45] offset:8704
	v_add_u32_e32 v2, s6, v236
	ds_read_b64 v[2:3], v2
	v_lshlrev_b32_e32 v4, 16, v46
	v_and_b32_e32 v5, 0xffff0000, v46
	v_lshlrev_b32_e32 v6, 16, v47
	v_and_b32_e32 v7, 0xffff0000, v47
	v_lshlrev_b32_e32 v8, 16, v48
	v_and_b32_e32 v9, 0xffff0000, v48
	v_lshlrev_b32_e32 v10, 16, v49
	v_and_b32_e32 v11, 0xffff0000, v49
	s_waitcnt lgkmcnt(0)
	v_pk_add_f32 v[4:5], v[4:5], v[2:3] op_sel_hi:[1,0] neg_lo:[0,1] neg_hi:[0,1]
	v_pk_add_f32 v[6:7], v[6:7], v[2:3] op_sel_hi:[1,0] neg_lo:[0,1] neg_hi:[0,1]
	v_pk_add_f32 v[8:9], v[8:9], v[2:3] op_sel_hi:[1,0] neg_lo:[0,1] neg_hi:[0,1]
	v_pk_add_f32 v[10:11], v[10:11], v[2:3] op_sel_hi:[1,0] neg_lo:[0,1] neg_hi:[0,1]
	v_pk_mul_f32 v[4:5], v[2:3], v[4:5] op_sel:[1,0]
	v_pk_mul_f32 v[6:7], v[2:3], v[6:7] op_sel:[1,0]
	v_pk_mul_f32 v[8:9], v[2:3], v[8:9] op_sel:[1,0]
	v_pk_mul_f32 v[2:3], v[2:3], v[10:11] op_sel:[1,0]
	v_pk_fma_f32 v[4:5], v[70:71], v[4:5], v[78:79]
	v_pk_fma_f32 v[6:7], v[72:73], v[6:7], v[80:81]
	v_pk_fma_f32 v[8:9], v[66:67], v[8:9], v[74:75]
	v_pk_fma_f32 v[10:11], v[68:69], v[2:3], v[76:77]
	v_cvt_pk_bf16_f32 v2, v4, v5
	v_cvt_pk_bf16_f32 v3, v6, v7
	v_cvt_pk_bf16_f32 v4, v8, v9
	v_cvt_pk_bf16_f32 v5, v10, v11
	ds_write_b128 v1, v[2:5] offset:45056
	ds_write_b128 v239, v[50:53] offset:17408
	v_add_u32_e32 v2, s6, v237
	ds_read_b64 v[2:3], v2
	v_lshlrev_b32_e32 v4, 16, v54
	v_and_b32_e32 v5, 0xffff0000, v54
	v_lshlrev_b32_e32 v6, 16, v55
	v_and_b32_e32 v7, 0xffff0000, v55
	v_lshlrev_b32_e32 v8, 16, v56
	v_and_b32_e32 v9, 0xffff0000, v56
	v_lshlrev_b32_e32 v10, 16, v57
	v_and_b32_e32 v11, 0xffff0000, v57
	s_waitcnt lgkmcnt(0)
	v_pk_add_f32 v[4:5], v[4:5], v[2:3] op_sel_hi:[1,0] neg_lo:[0,1] neg_hi:[0,1]
	v_pk_add_f32 v[6:7], v[6:7], v[2:3] op_sel_hi:[1,0] neg_lo:[0,1] neg_hi:[0,1]
	v_pk_add_f32 v[8:9], v[8:9], v[2:3] op_sel_hi:[1,0] neg_lo:[0,1] neg_hi:[0,1]
	v_pk_add_f32 v[10:11], v[10:11], v[2:3] op_sel_hi:[1,0] neg_lo:[0,1] neg_hi:[0,1]
	v_pk_mul_f32 v[4:5], v[2:3], v[4:5] op_sel:[1,0]
	v_pk_mul_f32 v[6:7], v[2:3], v[6:7] op_sel:[1,0]
	v_pk_mul_f32 v[8:9], v[2:3], v[8:9] op_sel:[1,0]
	v_pk_mul_f32 v[2:3], v[2:3], v[10:11] op_sel:[1,0]
	v_pk_fma_f32 v[4:5], v[70:71], v[4:5], v[78:79]
	v_pk_fma_f32 v[6:7], v[72:73], v[6:7], v[80:81]
	v_pk_fma_f32 v[8:9], v[66:67], v[8:9], v[74:75]
	v_pk_fma_f32 v[10:11], v[68:69], v[2:3], v[76:77]
	v_cvt_pk_bf16_f32 v2, v4, v5
	v_cvt_pk_bf16_f32 v3, v6, v7
	v_cvt_pk_bf16_f32 v4, v8, v9
	v_cvt_pk_bf16_f32 v5, v10, v11
	ds_write_b128 v1, v[2:5] offset:55296
	ds_write_b128 v239, v[58:61] offset:26112
	v_add_u32_e32 v1, s6, v238
	ds_read_b64 v[2:3], v1
	v_lshlrev_b32_e32 v4, 16, v62
	v_and_b32_e32 v5, 0xffff0000, v62
	v_lshlrev_b32_e32 v6, 16, v63
	v_and_b32_e32 v7, 0xffff0000, v63
	v_lshlrev_b32_e32 v8, 16, v64
	v_and_b32_e32 v9, 0xffff0000, v64
	v_lshlrev_b32_e32 v10, 16, v65
	v_and_b32_e32 v11, 0xffff0000, v65
	s_waitcnt lgkmcnt(0)
	v_pk_add_f32 v[4:5], v[4:5], v[2:3] op_sel_hi:[1,0] neg_lo:[0,1] neg_hi:[0,1]
	v_pk_add_f32 v[6:7], v[6:7], v[2:3] op_sel_hi:[1,0] neg_lo:[0,1] neg_hi:[0,1]
	v_pk_add_f32 v[8:9], v[8:9], v[2:3] op_sel_hi:[1,0] neg_lo:[0,1] neg_hi:[0,1]
	v_pk_add_f32 v[10:11], v[10:11], v[2:3] op_sel_hi:[1,0] neg_lo:[0,1] neg_hi:[0,1]
	v_pk_mul_f32 v[4:5], v[2:3], v[4:5] op_sel:[1,0]
	v_pk_mul_f32 v[6:7], v[2:3], v[6:7] op_sel:[1,0]
	v_pk_mul_f32 v[8:9], v[2:3], v[8:9] op_sel:[1,0]
	v_pk_mul_f32 v[2:3], v[2:3], v[10:11] op_sel:[1,0]
	v_pk_fma_f32 v[4:5], v[70:71], v[4:5], v[78:79]
	v_pk_fma_f32 v[6:7], v[72:73], v[6:7], v[80:81]
	v_pk_fma_f32 v[8:9], v[66:67], v[8:9], v[74:75]
	v_pk_fma_f32 v[10:11], v[68:69], v[2:3], v[76:77]
	v_cvt_pk_bf16_f32 v2, v4, v5
	v_cvt_pk_bf16_f32 v3, v6, v7
	v_cvt_pk_bf16_f32 v4, v8, v9
	v_cvt_pk_bf16_f32 v5, v10, v11
	s_cmpk_eq_i32 s54, 0x600
	ds_write_b128 v240, v[2:5] offset:55296
	s_waitcnt lgkmcnt(0)
	s_barrier
	s_cbranch_scc1 .LBB0_532
	v_lshl_add_u64 v[2:3], s[86:87], 0, v[194:195]
	v_lshl_add_u64 v[4:5], s[86:87], 0, v[198:199]
	global_load_dwordx4 v[34:37], v[2:3], off
	global_load_dwordx4 v[38:41], v[4:5], off
	v_lshl_add_u64 v[2:3], s[86:87], 0, v[190:191]
	v_lshl_add_u64 v[4:5], s[86:87], 0, v[200:201]
	global_load_dwordx4 v[42:45], v[2:3], off
	global_load_dwordx4 v[46:49], v[4:5], off
	v_lshl_add_u64 v[2:3], s[86:87], 0, v[188:189]
	v_lshl_add_u64 v[4:5], s[86:87], 0, v[202:203]
	global_load_dwordx4 v[50:53], v[2:3], off
	global_load_dwordx4 v[54:57], v[4:5], off
	v_lshl_add_u64 v[2:3], s[86:87], 0, v[186:187]
	v_lshl_add_u64 v[4:5], s[86:87], 0, v[204:205]
	global_load_dwordx4 v[58:61], v[2:3], off
	global_load_dwordx4 v[62:65], v[4:5], off
	v_lshl_add_u64 v[2:3], v[180:181], 0, s[54:55]
	global_load_dwordx4 v[66:69], v[2:3], off offset:528
	global_load_dwordx4 v[70:73], v[2:3], off offset:512
	v_lshl_add_u64 v[2:3], v[182:183], 0, s[54:55]
	global_load_dwordx4 v[74:77], v[2:3], off offset:528
	global_load_dwordx4 v[78:81], v[2:3], off offset:512
; #define LAS __attribute__((address_space(3)))
; DI s16x4 vtr(const LAS char* p) { return __builtin_bit_cast(s16x4, __builtin_amdgcn_ds_read_tr16_b64_v4i16((LAS v4i16_t*)p)); }
; DI void gmlp_unit(LAS char* lds, bf16_t* zU, const bf16_t* zV, const float* g_ln, const float* b_ln, const bf16_t* Wb, const float* b_sp, int R0, bool dummy = false) {
;     ...
;         const LAS char* vb_ = Vn + (8 * h + q4) * VP + cb * 64 + blk * 32 + p4 * 8;
;         bf16x8 af[8], b0f[8], b1f[8];
; #pragma unroll
;         for (int ss = 0; ss < 8; ++ss) {
;             if (16 * ss <= 32 * tb1 + 31) {
;                 const s16x4 lo = vtr(vb_ + (16 * ss) * VP), hi = vtr(vb_ + (16 * ss + 4) * VP);
;                 af[ss] = (bf16x8){lo[0], lo[1], lo[2], lo[3], hi[0], hi[1], hi[2], hi[3]};
;                 b1f[ss] = *(const LAS bf16x8*)(Wl + (32 * tb1 + r) * WP + (16 * ss + 8 * h) * 2);
;                 if (16 * ss <= 32 * tb0 + 31) b0f[ss] = *(const LAS bf16x8*)(Wl + (32 * tb0 + r) * WP + (16 * ss + 8 * h) * 2); } }
.LBB0_532:
	v_cndmask_b32_e64 v1, 0, 1, s[94:95]
	v_cmp_ne_u32_e64 s[6:7], 1, v1
	s_andn2_b64 vcc, exec, s[94:95]
	s_cbranch_vccnz .LBB0_535
	ds_read_b64_tr_b16 v[174:175], v231 offset:34816
	ds_read_b64_tr_b16 v[176:177], v231 offset:36096
	ds_read_b128 v[146:149], v241 offset:8704
	ds_read_b128 v[110:113], v241
	s_and_b64 vcc, exec, s[6:7]
	s_cbranch_vccz .LBB0_536
